# prompt attention fast loop: Q fragments hoisted into registers for the whole unit (four fewer ds_read_b128 per tile per wave), lgkmcnt ladder re-derived
# speedup vs baseline: 1.0541x; 1.0051x over previous
.LBB0_448:
	s_or_b64 exec, exec, s[34:35]
	s_xor_b64 s[34:35], s[20:21], -1
	s_and_b64 s[20:21], s[20:21], exec
	v_add_u32_e32 v6, 0x200, v2
	v_add_u32_e32 v14, 0x400, v2
	v_add_u32_e32 v16, 0x600, v2
	s_cselect_b32 s20, s63, s64
	v_ashrrev_i32_e32 v23, 4, v2
	v_ashrrev_i32_e32 v28, 4, v6
	v_ashrrev_i32_e32 v30, 4, v14
	v_ashrrev_i32_e32 v32, 4, v16
	s_lshl_b32 s38, s20, 7
	v_min_i32_e32 v4, 0x7f, v23
	v_min_i32_e32 v6, 0x7f, v28
	v_min_i32_e32 v14, 0x7f, v30
	v_min_i32_e32 v16, 0x7f, v32
	v_lshlrev_b32_e32 v0, 4, v2
	v_add_u32_e32 v4, s38, v4
	v_add_u32_e32 v6, s38, v6
	v_add_u32_e32 v14, s38, v14
	v_add_u32_e32 v16, s38, v16
	v_and_b32_e32 v0, 0xf0, v0
	v_ashrrev_i32_e32 v5, 31, v4
	v_ashrrev_i32_e32 v7, 31, v6
	v_ashrrev_i32_e32 v15, 31, v14
	v_ashrrev_i32_e32 v17, 31, v16
	v_lshl_add_u64 v[12:13], s[10:11], 0, v[0:1]
	v_lshlrev_b64 v[4:5], 11, v[4:5]
	v_lshlrev_b64 v[6:7], 11, v[6:7]
	v_lshlrev_b64 v[14:15], 11, v[14:15]
	v_lshlrev_b64 v[16:17], 11, v[16:17]
	v_lshl_add_u64 v[4:5], v[12:13], 0, v[4:5]
	v_lshl_add_u64 v[8:9], v[12:13], 0, v[6:7]
	v_lshl_add_u64 v[14:15], v[12:13], 0, v[14:15]
	v_lshl_add_u64 v[16:17], v[12:13], 0, v[16:17]
	global_load_dwordx4 v[4:7], v[4:5], off
	s_nop 0
	global_load_dwordx4 v[8:11], v[8:9], off
	s_nop 0
	global_load_dwordx4 v[12:15], v[14:15], off
	s_nop 0
	global_load_dwordx4 v[16:19], v[16:17], off
	v_ashrrev_i32_e32 v20, 3, v2
	v_ashrrev_i32_e32 v21, 31, v20
	v_lshlrev_b32_e32 v26, 5, v2
	s_add_i32 s20, 0, 0x11000
	v_lshlrev_b64 v[24:25], 11, v[20:21]
	v_add_u32_e32 v22, s20, v0
	v_and_b32_e32 v0, 0xe0, v26
	v_lshl_add_u64 v[24:25], s[12:13], 0, v[24:25]
	v_mad_u64_u32 v[26:27], s[20:21], v23, s51, v[22:23]
	v_lshl_add_u64 v[24:25], v[24:25], 0, v[0:1]
	v_mad_u64_u32 v[28:29], s[20:21], v28, s51, v[22:23]
	v_mad_u64_u32 v[30:31], s[20:21], v30, s51, v[22:23]
	v_mad_u64_u32 v[22:23], s[20:21], v32, s51, v[22:23]
	v_lshlrev_b32_e32 v3, 4, v3
	v_and_b32_e32 v165, 31, v2
	s_lshl_b32 s39, s65, 5
	s_ashr_i32 s40, s65, 2
	s_and_b32 s20, s39, 0x60
	v_or_b32_e32 v174, s20, v165
	s_lshl_b32 s41, s40, 7
	s_or_b32 s21, s38, 0x7f
	v_mov_b32_e32 v79, 0
	s_cmpk_lt_i32 s21, 0xffc1
	v_mov_b32_e32 v78, 0
	v_mov_b32_e32 v77, 0
	v_mov_b32_e32 v76, 0
	v_mov_b32_e32 v75, 0
	v_mov_b32_e32 v74, 0
	v_mov_b32_e32 v73, 0
	v_mov_b32_e32 v72, 0
	v_mov_b32_e32 v71, 0
	v_mov_b32_e32 v70, 0
	v_mov_b32_e32 v69, 0
	v_mov_b32_e32 v68, 0
	v_mov_b32_e32 v67, 0
	v_mov_b32_e32 v66, 0
	v_mov_b32_e32 v65, 0
	v_mov_b32_e32 v64, v79
	v_mov_b32_e32 v63, 0
	v_mov_b32_e32 v62, 0
	v_mov_b32_e32 v61, 0
	v_mov_b32_e32 v60, 0
	v_mov_b32_e32 v59, 0
	v_mov_b32_e32 v58, 0
	v_mov_b32_e32 v57, 0
	v_mov_b32_e32 v56, 0
	v_mov_b32_e32 v55, 0
	v_mov_b32_e32 v54, 0
	s_waitcnt vmcnt(3)
	ds_write_b128 v26, v[4:7]
	s_waitcnt vmcnt(2)
	ds_write_b128 v28, v[8:11]
	s_waitcnt vmcnt(1)
	ds_write_b128 v30, v[12:15]
	s_waitcnt vmcnt(0)
	ds_write_b128 v22, v[16:19]
	global_load_dwordx4 v[4:7], v[24:25], off
	global_load_dwordx4 v[8:11], v[24:25], off offset:16
	v_bfe_u32 v12, v2, 2, 4
	v_ashrrev_i32_e32 v14, 5, v2
	v_and_or_b32 v3, v3, 16, v12
	v_bfi_b32 v16, -4, v14, v2
	v_mov_b32_e32 v13, v1
	v_mul_lo_u32 v15, v20, s51
	v_lshlrev_b32_e32 v12, 12, v3
	v_lshlrev_b32_e32 v14, 3, v16
	v_add_u32_e32 v17, 0, v15
	v_lshl_add_u64 v[12:13], s[14:15], 0, v[12:13]
	v_ashrrev_i32_e32 v15, 31, v14
	v_add_u32_e32 v176, v17, v0
	v_lshl_add_u64 v[12:13], v[14:15], 1, v[12:13]
	v_bfe_u32 v0, v2, 5, 1
	v_mul_lo_u32 v2, v16, s56
	v_lshlrev_b32_e32 v3, 2, v3
	v_add_u32_e32 v2, 0, v2
	v_add_u32_e32 v177, v2, v3
	v_add_u32_e32 v178, 0x8800, v177
	v_lshl_add_u64 v[166:167], v[24:25], 0, s[4:5]
	v_lshlrev_b32_e32 v173, 4, v0
	v_lshlrev_b32_e32 v164, 3, v0
	v_mov_b32_e32 v53, 0
	v_mov_b32_e32 v52, 0
	v_mov_b32_e32 v51, 0
	v_mov_b32_e32 v50, 0
	v_mov_b32_e32 v49, 0
	v_mov_b32_e32 v48, v79
	v_mov_b32_e32 v47, 0
	v_mov_b32_e32 v46, 0
	v_mov_b32_e32 v45, 0
	v_mov_b32_e32 v44, 0
	v_mov_b32_e32 v43, 0
	v_mov_b32_e32 v42, 0
	v_mov_b32_e32 v41, 0
	v_mov_b32_e32 v40, 0
	v_mov_b32_e32 v39, 0
	v_mov_b32_e32 v38, 0
	v_mov_b32_e32 v37, 0
	v_mov_b32_e32 v36, 0
	v_mov_b32_e32 v35, 0
	v_mov_b32_e32 v34, 0
	v_mov_b32_e32 v33, 0
	v_mov_b32_e32 v32, v79
	v_mov_b32_e32 v31, 0
	v_mov_b32_e32 v30, 0
	v_mov_b32_e32 v29, 0
	v_mov_b32_e32 v28, 0
	v_mov_b32_e32 v27, 0
	v_mov_b32_e32 v26, 0
	v_mov_b32_e32 v25, 0
	s_waitcnt vmcnt(1)
	ds_write_b128 v176, v[4:7]
	s_waitcnt vmcnt(0)
	ds_write_b128 v176, v[8:11] offset:16
	global_load_dwordx4 v[4:7], v[12:13], off
	global_load_dwordx4 v[8:11], v[12:13], off offset:2048
	v_lshl_add_u64 v[168:169], v[12:13], 0, s[4:5]
	v_mov_b32_e32 v24, 0
	v_mov_b32_e32 v23, 0
	v_mov_b32_e32 v22, 0
	v_mov_b32_e32 v21, 0
	v_mov_b32_e32 v20, 0
	v_mov_b32_e32 v19, 0
	v_mov_b32_e32 v18, 0
	v_mov_b32_e32 v17, 0
	v_mov_b32_e32 v16, v79
	v_mov_b32_e32 v175, 0
	s_waitcnt vmcnt(1)
	v_and_b32_e32 v2, 0xffff, v4
	v_lshrrev_b32_e32 v3, 16, v4
	v_and_b32_e32 v4, 0xffff, v5
	v_lshrrev_b32_e32 v5, 16, v5
	v_and_b32_e32 v12, 0xffff, v6
	v_lshrrev_b32_e32 v6, 16, v6
	v_and_b32_e32 v13, 0xffff, v7
	v_lshrrev_b32_e32 v7, 16, v7
	s_waitcnt vmcnt(0)
	v_lshl_or_b32 v2, v8, 16, v2
	v_and_or_b32 v3, v8, s57, v3
	v_lshl_or_b32 v4, v9, 16, v4
	v_and_or_b32 v5, v9, s57, v5
	v_lshl_or_b32 v8, v10, 16, v12
	v_and_or_b32 v6, v10, s57, v6
	v_lshl_or_b32 v9, v11, 16, v13
	v_and_or_b32 v7, v11, s57, v7
	ds_write2_b32 v178, v2, v3 offset1:34
	ds_write2_b32 v178, v4, v5 offset0:68 offset1:102
	ds_write2_b32 v178, v8, v6 offset0:136 offset1:170
	ds_write2_b32 v178, v9, v7 offset0:204 offset1:238
	global_load_dwordx4 v[120:123], v[166:167], off offset:16
	global_load_dwordx4 v[124:127], v[166:167], off
	global_load_dwordx4 v[116:119], v[168:169], off
	global_load_dwordx4 v[112:115], v[168:169], off offset:2048
	v_mul_u32_u24_e32 v2, 0x110, v174
	v_or_b32_e32 v3, s41, v173
	v_add3_u32 v179, v3, v2, s50
	v_mul_u32_u24_e32 v2, 0x88, v165
	v_mul_u32_u24_e32 v3, 0x110, v165
	v_add3_u32 v2, v2, v164, s58
	v_add3_u32 v180, v173, v3, s41
	s_waitcnt lgkmcnt(0)
	s_barrier
	s_cbranch_scc1 .LBB0_465
	s_ashr_i32 s41, s21, 31
	v_lshlrev_b32_e32 v0, 2, v0
	s_lshr_b32 s41, s41, 26
	v_sub_u32_e32 v0, v0, v165
	s_add_i32 s21, s21, s41
	v_subrev_u32_e32 v0, s20, v0
	v_mov_b32_e32 v14, v1
	v_mov_b32_e32 v15, v1
	s_ashr_i32 s21, s21, 6
	s_or_b32 s42, s20, s38
	v_add_u32_e32 v181, 0, v2
	v_subrev_u32_e32 v182, s38, v0
	v_mov_b32_e32 v0, v1
	v_mov_b32_e32 v2, v1
	v_mov_b32_e32 v3, v1
	v_mov_b32_e32 v4, v1
	v_mov_b32_e32 v5, v1
	v_mov_b32_e32 v6, v1
	v_mov_b32_e32 v7, v1
	v_mov_b32_e32 v8, v1
	v_mov_b32_e32 v9, v1
	v_mov_b32_e32 v10, v1
	v_mov_b32_e32 v11, v1
	v_mov_b32_e32 v12, v1
	v_mov_b32_e32 v13, v1
	v_mov_b64_e32 v[30:31], v[14:15]
	v_mov_b64_e32 v[46:47], v[14:15]
	v_mov_b64_e32 v[62:63], v[14:15]
	v_mov_b64_e32 v[78:79], v[14:15]
	s_min_i32 s41, s21, 0xff
	s_ashr_i32 s43, s42, 6
	s_mov_b32 s44, 0
	v_mov_b32_e32 v175, 0
	s_movk_i32 s45, 0xda
	v_mov_b64_e32 v[28:29], v[12:13]
	v_mov_b64_e32 v[26:27], v[10:11]
	v_mov_b64_e32 v[24:25], v[8:9]
	v_mov_b64_e32 v[22:23], v[6:7]
	v_mov_b64_e32 v[20:21], v[4:5]
	v_mov_b64_e32 v[18:19], v[2:3]
	v_mov_b64_e32 v[16:17], v[0:1]
	v_mov_b64_e32 v[44:45], v[12:13]
	v_mov_b64_e32 v[42:43], v[10:11]
	v_mov_b64_e32 v[40:41], v[8:9]
	v_mov_b64_e32 v[38:39], v[6:7]
	v_mov_b64_e32 v[36:37], v[4:5]
	v_mov_b64_e32 v[34:35], v[2:3]
	v_mov_b64_e32 v[32:33], v[0:1]
	v_mov_b64_e32 v[60:61], v[12:13]
	v_mov_b64_e32 v[58:59], v[10:11]
	v_mov_b64_e32 v[56:57], v[8:9]
	v_mov_b64_e32 v[54:55], v[6:7]
	v_mov_b64_e32 v[52:53], v[4:5]
	v_mov_b64_e32 v[50:51], v[2:3]
	v_mov_b64_e32 v[48:49], v[0:1]
	v_mov_b64_e32 v[76:77], v[12:13]
	v_mov_b64_e32 v[74:75], v[10:11]
	v_mov_b64_e32 v[72:73], v[8:9]
	v_mov_b64_e32 v[70:71], v[6:7]
	v_mov_b64_e32 v[68:69], v[4:5]
	v_mov_b64_e32 v[66:67], v[2:3]
	v_mov_b64_e32 v[64:65], v[0:1]
	v_cmp_gt_f32_e32 vcc, 0xc2700000, v171
	s_cbranch_vccnz .LBB0_451
	s_mov_b32 s100, 0x05040100
	s_mov_b32 s101, 0x07060302
	ds_read_b128 v[234:237], v179
	ds_read_b128 v[238:241], v179 offset:32
	ds_read_b128 v[244:247], v179 offset:64
	ds_read_b128 v[248:251], v179 offset:96
	s_waitcnt lgkmcnt(0)
	s_branch .Lqf_451

.Lqf_451:
	v_lshl_add_u64 v[166:167], v[166:167], 0, s[4:5]
	v_lshl_add_u64 v[14:15], v[168:169], 0, s[4:5]
	global_load_dwordx4 v[10:13], v[166:167], off offset:16
	global_load_dwordx4 v[128:131], v[166:167], off
	global_load_dwordx4 v[2:5], v[14:15], off
	global_load_dwordx4 v[6:9], v[14:15], off offset:2048
	s_cmp_le_i32 s44, s43
	s_cselect_b64 s[20:21], -1, 0
	s_cmp_gt_i32 s44, s43
	s_cbranch_scc1 .Lqf_455
	ds_read_b128 v[80:83], v180
	ds_read_b128 v[136:139], v180 offset:32
	ds_read_b128 v[100:103], v180 offset:8704
	ds_read_b128 v[140:143], v180 offset:8736
	s_sub_i32 s68, s45, 64
	s_cmp_le_i32 s68, s42
	s_waitcnt lgkmcnt(3)
	v_mfma_f32_32x32x16_bf16 v[80:95], v[80:83], v[234:237], 0
	s_waitcnt lgkmcnt(1)
	v_mfma_f32_32x32x16_bf16 v[96:111], v[100:103], v[234:237], 0
	s_waitcnt lgkmcnt(2)
	v_mfma_f32_32x32x16_bf16 v[80:95], v[136:139], v[238:241], v[80:95]
	s_waitcnt lgkmcnt(0)
	v_mfma_f32_32x32x16_bf16 v[96:111], v[140:143], v[238:241], v[96:111]
	ds_read_b128 v[132:135], v180 offset:64
	ds_read_b128 v[144:147], v180 offset:96
	s_waitcnt lgkmcnt(1)
	v_mfma_f32_32x32x16_bf16 v[80:95], v[132:135], v[244:247], v[80:95]
	ds_read_b128 v[132:135], v180 offset:8768
	ds_read_b128 v[184:187], v180 offset:8800
	s_waitcnt lgkmcnt(1)
	v_mfma_f32_32x32x16_bf16 v[96:111], v[132:135], v[244:247], v[96:111]
	s_waitcnt lgkmcnt(2)
	v_mfma_f32_32x32x16_bf16 v[80:95], v[144:147], v[248:251], v[80:95]
	s_waitcnt lgkmcnt(0)
	v_mfma_f32_32x32x16_bf16 v[96:111], v[184:187], v[248:251], v[96:111]
	s_cbranch_scc1 .Lqf_454
	v_add_u32_e32 v0, s45, v182
	v_add_u32_e32 v134, 0xffffff27, v0
	s_add_i32 s68, 0, 0x19800
	v_max_i32_e32 v134, 0xffffff80, v134
	v_lshl_add_u32 v136, v134, 2, s68
	v_add_u32_e32 v134, 0xffffff28, v0
	v_add_u32_e32 v132, 0xffffff26, v0
	v_add_u32_e32 v133, 0xffffff46, v0
	v_add_u32_e32 v135, 0xffffff47, v0
	v_add_u32_e32 v137, 0xffffff48, v0
	v_max_i32_e32 v134, 0xffffff80, v134
	v_add_u32_e32 v139, 0xffffff49, v0
	v_max_i32_e32 v132, 0xffffff80, v132
	v_max_i32_e32 v133, 0xffffff80, v133
	v_max_i32_e32 v135, 0xffffff80, v135
	v_max_i32_e32 v137, 0xffffff80, v137
	v_lshl_add_u32 v138, v134, 2, s68
	v_add_u32_e32 v134, 0xffffff29, v0
	v_max_i32_e32 v139, 0xffffff80, v139
	v_lshl_add_u32 v132, v132, 2, s68
	v_lshl_add_u32 v133, v133, 2, s68
	v_lshl_add_u32 v135, v135, 2, s68
	v_lshl_add_u32 v137, v137, 2, s68
	v_max_i32_e32 v134, 0xffffff80, v134
	v_lshl_add_u32 v139, v139, 2, s68
	v_lshl_add_u32 v140, v134, 2, s68
	ds_read_b32 v132, v132 offset:512
	ds_read_b32 v134, v133 offset:512
	ds_read_b32 v133, v136 offset:512
	ds_read_b32 v135, v135 offset:512
	ds_read_b32 v136, v138 offset:512
	ds_read_b32 v138, v137 offset:512
	ds_read_b32 v137, v140 offset:512
	ds_read_b32 v139, v139 offset:512
	v_add_u32_e32 v142, 0xffffff2f, v0
	v_max_i32_e32 v142, 0xffffff80, v142
	v_lshl_add_u32 v144, v142, 2, s68
	v_add_u32_e32 v142, 0xffffff30, v0
	v_add_u32_e32 v140, 0xffffff2e, v0
	v_add_u32_e32 v141, 0xffffff4e, v0
	v_add_u32_e32 v143, 0xffffff4f, v0
	v_add_u32_e32 v145, 0xffffff50, v0
	v_max_i32_e32 v142, 0xffffff80, v142
	v_add_u32_e32 v147, 0xffffff51, v0
	v_max_i32_e32 v140, 0xffffff80, v140
	v_max_i32_e32 v141, 0xffffff80, v141
	v_max_i32_e32 v143, 0xffffff80, v143
	v_max_i32_e32 v145, 0xffffff80, v145
	v_lshl_add_u32 v146, v142, 2, s68
	v_add_u32_e32 v142, 0xffffff31, v0
	v_max_i32_e32 v147, 0xffffff80, v147
	v_lshl_add_u32 v140, v140, 2, s68
	v_lshl_add_u32 v141, v141, 2, s68
	v_lshl_add_u32 v143, v143, 2, s68
	v_lshl_add_u32 v145, v145, 2, s68
	v_max_i32_e32 v142, 0xffffff80, v142
	v_lshl_add_u32 v147, v147, 2, s68
	v_lshl_add_u32 v168, v142, 2, s68
	ds_read_b32 v140, v140 offset:512
	ds_read_b32 v142, v141 offset:512
	ds_read_b32 v141, v144 offset:512
	ds_read_b32 v143, v143 offset:512
	ds_read_b32 v144, v146 offset:512
	ds_read_b32 v146, v145 offset:512
	ds_read_b32 v145, v168 offset:512
	ds_read_b32 v147, v147 offset:512
	v_add_u32_e32 v184, 0xffffff57, v0
	v_max_i32_e32 v184, 0xffffff80, v184
	v_lshl_add_u32 v185, v184, 2, s68
	v_add_u32_e32 v184, 0xffffff38, v0
	v_add_u32_e32 v186, 0xffffff58, v0
	v_max_i32_e32 v184, 0xffffff80, v184
	v_add_u32_e32 v168, 0xffffff36, v0
	v_add_u32_e32 v169, 0xffffff56, v0
	v_max_i32_e32 v186, 0xffffff80, v186
	v_lshl_add_u32 v187, v184, 2, s68
	v_add_u32_e32 v184, 0xffffff39, v0
	v_max_i32_e32 v168, 0xffffff80, v168
	v_max_i32_e32 v169, 0xffffff80, v169
	v_add_u32_e32 v183, 0xffffff37, v0
	v_lshl_add_u32 v188, v186, 2, s68
	v_add_u32_e32 v186, 0xffffff59, v0
	v_max_i32_e32 v184, 0xffffff80, v184
	v_lshl_add_u32 v168, v168, 2, s68
	v_lshl_add_u32 v169, v169, 2, s68
	v_max_i32_e32 v183, 0xffffff80, v183
	v_max_i32_e32 v186, 0xffffff80, v186
	v_lshl_add_u32 v189, v184, 2, s68
	v_lshl_add_u32 v183, v183, 2, s68
	v_lshl_add_u32 v190, v186, 2, s68
	ds_read_b32 v168, v168 offset:512
	ds_read_b32 v184, v169 offset:512
	ds_read_b32 v169, v183 offset:512
	ds_read_b32 v185, v185 offset:512
	ds_read_b32 v186, v187 offset:512
	ds_read_b32 v188, v188 offset:512
	ds_read_b32 v187, v189 offset:512
	ds_read_b32 v189, v190 offset:512
	v_add_u32_e32 v183, 0xffffff3e, v0
	v_add_u32_e32 v190, 0xffffff5e, v0
	v_max_i32_e32 v183, 0xffffff80, v183
	v_add_u32_e32 v191, 0xffffff3f, v0
	v_add_u32_e32 v192, 0xffffff5f, v0
	v_add_u32_e32 v193, 0xffffff40, v0
	v_add_u32_e32 v196, 0xffffff60, v0
	v_add_u32_e32 v197, 0xffffff41, v0
	v_add_u32_e32 v0, 0xffffff61, v0
	v_max_i32_e32 v190, 0xffffff80, v190
	v_lshl_add_u32 v183, v183, 2, s68
	v_max_i32_e32 v191, 0xffffff80, v191
	v_max_i32_e32 v192, 0xffffff80, v192
	v_max_i32_e32 v193, 0xffffff80, v193
	v_max_i32_e32 v196, 0xffffff80, v196
	v_max_i32_e32 v197, 0xffffff80, v197
	v_max_i32_e32 v0, 0xffffff80, v0
	v_lshl_add_u32 v190, v190, 2, s68
	v_lshl_add_u32 v191, v191, 2, s68
	v_lshl_add_u32 v192, v192, 2, s68
	v_lshl_add_u32 v193, v193, 2, s68
	v_lshl_add_u32 v196, v196, 2, s68
	v_lshl_add_u32 v197, v197, 2, s68
	s_waitcnt lgkmcnt(14)
	v_pk_add_f32 v[82:83], v[82:83], v[136:137]
	v_pk_add_f32 v[80:81], v[80:81], v[132:133]
	s_waitcnt lgkmcnt(9)
	v_pk_add_f32 v[86:87], v[86:87], v[144:145]
	v_pk_add_f32 v[84:85], v[84:85], v[140:141]
	v_lshl_add_u32 v0, v0, 2, s68
	ds_read_b32 v132, v183 offset:512
	ds_read_b32 v136, v190 offset:512
	ds_read_b32 v140, v193 offset:512
	ds_read_b32 v141, v197 offset:512
	ds_read_b32 v133, v191 offset:512
	ds_read_b32 v137, v192 offset:512
	ds_read_b32 v144, v196 offset:512
	ds_read_b32 v145, v0 offset:512
	s_waitcnt lgkmcnt(9)
	v_pk_add_f32 v[90:91], v[90:91], v[186:187]
	v_pk_add_f32 v[88:89], v[88:89], v[168:169]
	s_waitcnt lgkmcnt(4)
	v_pk_add_f32 v[94:95], v[94:95], v[140:141]
	s_waitcnt lgkmcnt(3)
	v_pk_add_f32 v[92:93], v[92:93], v[132:133]
	v_pk_add_f32 v[98:99], v[98:99], v[138:139]
	v_pk_add_f32 v[96:97], v[96:97], v[134:135]
	v_pk_add_f32 v[102:103], v[102:103], v[146:147]
	v_pk_add_f32 v[100:101], v[100:101], v[142:143]
	v_pk_add_f32 v[106:107], v[106:107], v[188:189]
	v_pk_add_f32 v[104:105], v[104:105], v[184:185]
	s_waitcnt lgkmcnt(0)
	v_pk_add_f32 v[110:111], v[110:111], v[144:145]
	v_pk_add_f32 v[108:109], v[108:109], v[136:137]

.Lqf_457:
	s_waitcnt vmcnt(5)
	s_waitcnt vmcnt(4)
	v_perm_b32 v0, v112, v116, s100
	v_perm_b32 v80, v112, v116, s101
	v_add_u32_e32 v81, 0xcc00, v177
	ds_write2_b32 v81, v0, v80 offset1:34
	v_perm_b32 v0, v113, v117, s100
	v_perm_b32 v80, v113, v117, s101
	ds_write2_b32 v81, v0, v80 offset0:68 offset1:102
	v_perm_b32 v0, v114, v118, s100
	v_perm_b32 v80, v114, v118, s101
	ds_write2_b32 v81, v0, v80 offset0:136 offset1:170
	v_perm_b32 v0, v115, v119, s100
	v_perm_b32 v80, v115, v119, s101
	s_mov_b64 s[20:21], -1
	s_cmp_ge_i32 s44, s41
	v_readfirstlane_b32 s69, v0
	v_readfirstlane_b32 s68, v0
	ds_write2_b32 v81, v0, v80 offset0:204 offset1:238
	s_waitcnt lgkmcnt(0)
	s_barrier
	s_cbranch_scc1 .Lqf_450
	v_lshl_add_u64 v[166:167], v[166:167], 0, s[4:5]
	v_lshl_add_u64 v[168:169], v[14:15], 0, s[4:5]
	global_load_dwordx4 v[120:123], v[166:167], off offset:16
	global_load_dwordx4 v[124:127], v[166:167], off
	global_load_dwordx4 v[116:119], v[168:169], off
	global_load_dwordx4 v[112:115], v[168:169], off offset:2048
	s_cmp_lt_i32 s44, s43
	s_cselect_b64 s[20:21], -1, 0
	s_cmp_ge_i32 s44, s43
	s_cbranch_scc1 .Lqf_462
	ds_read_b128 v[80:83], v180 offset:17408
	ds_read_b128 v[152:155], v180 offset:17440
	ds_read_b128 v[100:103], v180 offset:26112
	ds_read_b128 v[156:159], v180 offset:26144
	s_cmp_le_i32 s45, s42
	s_waitcnt lgkmcnt(3)
	v_mfma_f32_32x32x16_bf16 v[80:95], v[80:83], v[234:237], 0
	s_waitcnt lgkmcnt(1)
	v_mfma_f32_32x32x16_bf16 v[96:111], v[100:103], v[234:237], 0
	s_waitcnt lgkmcnt(2)
	v_mfma_f32_32x32x16_bf16 v[80:95], v[152:155], v[238:241], v[80:95]
	s_waitcnt lgkmcnt(0)
	v_mfma_f32_32x32x16_bf16 v[96:111], v[156:159], v[238:241], v[96:111]
	ds_read_b128 v[148:151], v180 offset:17472
	ds_read_b128 v[160:163], v180 offset:17504
	s_waitcnt lgkmcnt(1)
	v_mfma_f32_32x32x16_bf16 v[80:95], v[148:151], v[244:247], v[80:95]
	ds_read_b128 v[148:151], v180 offset:26176
	ds_read_b128 v[184:187], v180 offset:26208
	s_waitcnt lgkmcnt(1)
	v_mfma_f32_32x32x16_bf16 v[96:111], v[148:151], v[244:247], v[96:111]
	s_waitcnt lgkmcnt(2)
	v_mfma_f32_32x32x16_bf16 v[80:95], v[160:163], v[248:251], v[80:95]
	s_waitcnt lgkmcnt(0)
	v_mfma_f32_32x32x16_bf16 v[96:111], v[184:187], v[248:251], v[96:111]
	s_cbranch_scc1 .Lqf_461
	v_add_u32_e32 v0, s45, v182
	v_add_u32_e32 v148, 0xffffff67, v0
	s_add_i32 s68, 0, 0x19800
	v_max_i32_e32 v148, 0xffffff80, v148
	v_lshl_add_u32 v150, v148, 2, s68
	v_add_u32_e32 v148, 0xffffff68, v0
	v_add_u32_e32 v14, 0xffffff66, v0
	v_add_u32_e32 v15, 0xffffff86, v0
	v_add_u32_e32 v149, 0xffffff87, v0
	v_add_u32_e32 v151, 0xffffff88, v0
	v_max_i32_e32 v148, 0xffffff80, v148
	v_add_u32_e32 v153, 0xffffff89, v0
	v_max_i32_e32 v14, 0xffffff80, v14
	v_max_i32_e32 v15, 0xffffff80, v15
	v_max_i32_e32 v149, 0xffffff80, v149
	v_max_i32_e32 v151, 0xffffff80, v151
	v_lshl_add_u32 v152, v148, 2, s68
	v_add_u32_e32 v148, 0xffffff69, v0
	v_max_i32_e32 v153, 0xffffff80, v153
	v_lshl_add_u32 v14, v14, 2, s68
	v_lshl_add_u32 v15, v15, 2, s68
	v_lshl_add_u32 v149, v149, 2, s68
	v_lshl_add_u32 v151, v151, 2, s68
	v_max_i32_e32 v148, 0xffffff80, v148
	v_lshl_add_u32 v153, v153, 2, s68
	v_lshl_add_u32 v154, v148, 2, s68
	ds_read_b32 v14, v14 offset:512
	ds_read_b32 v148, v15 offset:512
	ds_read_b32 v15, v150 offset:512
	ds_read_b32 v149, v149 offset:512
	ds_read_b32 v150, v152 offset:512
	ds_read_b32 v152, v151 offset:512
	ds_read_b32 v151, v154 offset:512
	ds_read_b32 v153, v153 offset:512
	v_add_u32_e32 v156, 0xffffff6f, v0
	v_max_i32_e32 v156, 0xffffff80, v156
	v_lshl_add_u32 v158, v156, 2, s68
	v_add_u32_e32 v156, 0xffffff70, v0
	v_add_u32_e32 v154, 0xffffff6e, v0
	v_add_u32_e32 v155, 0xffffff8e, v0
	v_add_u32_e32 v157, 0xffffff8f, v0
	v_add_u32_e32 v159, 0xffffff90, v0
	v_max_i32_e32 v156, 0xffffff80, v156
	v_add_u32_e32 v161, 0xffffff91, v0
	v_max_i32_e32 v154, 0xffffff80, v154
	v_max_i32_e32 v155, 0xffffff80, v155
	v_max_i32_e32 v157, 0xffffff80, v157
	v_max_i32_e32 v159, 0xffffff80, v159
	v_lshl_add_u32 v160, v156, 2, s68
	v_add_u32_e32 v156, 0xffffff71, v0
	v_max_i32_e32 v161, 0xffffff80, v161
	v_lshl_add_u32 v154, v154, 2, s68
	v_lshl_add_u32 v155, v155, 2, s68
	v_lshl_add_u32 v157, v157, 2, s68
	v_lshl_add_u32 v159, v159, 2, s68
	v_max_i32_e32 v156, 0xffffff80, v156
	v_lshl_add_u32 v161, v161, 2, s68
	v_lshl_add_u32 v162, v156, 2, s68
	ds_read_b32 v154, v154 offset:512
	ds_read_b32 v156, v155 offset:512
	ds_read_b32 v155, v158 offset:512
	ds_read_b32 v157, v157 offset:512
	ds_read_b32 v158, v160 offset:512
	ds_read_b32 v160, v159 offset:512
	ds_read_b32 v159, v162 offset:512
	ds_read_b32 v161, v161 offset:512
	v_add_u32_e32 v184, 0xffffff97, v0
	v_max_i32_e32 v184, 0xffffff80, v184
	v_lshl_add_u32 v185, v184, 2, s68
	v_add_u32_e32 v184, 0xffffff78, v0
	v_add_u32_e32 v186, 0xffffff98, v0
	v_max_i32_e32 v184, 0xffffff80, v184
	v_add_u32_e32 v162, 0xffffff76, v0
	v_add_u32_e32 v163, 0xffffff96, v0
	v_max_i32_e32 v186, 0xffffff80, v186
	v_lshl_add_u32 v187, v184, 2, s68
	v_add_u32_e32 v184, 0xffffff79, v0
	v_max_i32_e32 v162, 0xffffff80, v162
	v_max_i32_e32 v163, 0xffffff80, v163
	v_add_u32_e32 v183, 0xffffff77, v0
	v_lshl_add_u32 v188, v186, 2, s68
	v_add_u32_e32 v186, 0xffffff99, v0
	v_max_i32_e32 v184, 0xffffff80, v184
	v_lshl_add_u32 v162, v162, 2, s68
	v_lshl_add_u32 v163, v163, 2, s68
	v_max_i32_e32 v183, 0xffffff80, v183
	v_max_i32_e32 v186, 0xffffff80, v186
	v_lshl_add_u32 v189, v184, 2, s68
	v_lshl_add_u32 v183, v183, 2, s68
	v_lshl_add_u32 v190, v186, 2, s68
	ds_read_b32 v162, v162 offset:512
	ds_read_b32 v184, v163 offset:512
	ds_read_b32 v163, v183 offset:512
	ds_read_b32 v185, v185 offset:512
	ds_read_b32 v186, v187 offset:512
	ds_read_b32 v188, v188 offset:512
	ds_read_b32 v187, v189 offset:512
	ds_read_b32 v189, v190 offset:512
	v_add_u32_e32 v183, 0xffffff7e, v0
	v_add_u32_e32 v190, 0xffffff9e, v0
	v_max_i32_e32 v183, 0xffffff80, v183
	v_add_u32_e32 v191, 0xffffff7f, v0
	v_add_u32_e32 v192, 0xffffff9f, v0
	v_add_u32_e32 v193, 0xffffff80, v0
	v_add_u32_e32 v196, 0xffffffa0, v0
	v_add_u32_e32 v197, 0xffffff81, v0
	v_add_u32_e32 v0, 0xffffffa1, v0
	v_max_i32_e32 v190, 0xffffff80, v190
	v_lshl_add_u32 v183, v183, 2, s68
	v_max_i32_e32 v191, 0xffffff80, v191
	v_max_i32_e32 v192, 0xffffff80, v192
	v_max_i32_e32 v193, 0xffffff80, v193
	v_max_i32_e32 v196, 0xffffff80, v196
	v_max_i32_e32 v197, 0xffffff80, v197
	v_max_i32_e32 v0, 0xffffff80, v0
	v_lshl_add_u32 v190, v190, 2, s68
	v_lshl_add_u32 v191, v191, 2, s68
	v_lshl_add_u32 v192, v192, 2, s68
	v_lshl_add_u32 v193, v193, 2, s68
	v_lshl_add_u32 v196, v196, 2, s68
	v_lshl_add_u32 v197, v197, 2, s68
	s_waitcnt lgkmcnt(14)
	v_pk_add_f32 v[82:83], v[82:83], v[150:151]
	v_pk_add_f32 v[80:81], v[80:81], v[14:15]
	s_waitcnt lgkmcnt(9)
	v_pk_add_f32 v[86:87], v[86:87], v[158:159]
	v_pk_add_f32 v[84:85], v[84:85], v[154:155]
	v_lshl_add_u32 v0, v0, 2, s68
	ds_read_b32 v14, v183 offset:512
	ds_read_b32 v150, v190 offset:512
	ds_read_b32 v154, v193 offset:512
	ds_read_b32 v155, v197 offset:512
	ds_read_b32 v15, v191 offset:512
	ds_read_b32 v151, v192 offset:512
	ds_read_b32 v158, v196 offset:512
	ds_read_b32 v159, v0 offset:512
	s_waitcnt lgkmcnt(9)
	v_pk_add_f32 v[90:91], v[90:91], v[186:187]
	v_pk_add_f32 v[88:89], v[88:89], v[162:163]
	s_waitcnt lgkmcnt(4)
	v_pk_add_f32 v[94:95], v[94:95], v[154:155]
	s_waitcnt lgkmcnt(3)
	v_pk_add_f32 v[92:93], v[92:93], v[14:15]
	v_pk_add_f32 v[98:99], v[98:99], v[152:153]
	v_pk_add_f32 v[96:97], v[96:97], v[148:149]
	v_pk_add_f32 v[102:103], v[102:103], v[160:161]
	v_pk_add_f32 v[100:101], v[100:101], v[156:157]
	v_pk_add_f32 v[106:107], v[106:107], v[188:189]
	v_pk_add_f32 v[104:105], v[104:105], v[184:185]
	s_waitcnt lgkmcnt(0)
	v_pk_add_f32 v[110:111], v[110:111], v[158:159]
	v_pk_add_f32 v[108:109], v[108:109], v[150:151]
